# ln1_route router dot products: 64 weight-row ds_read_b128 per token pipelined 8 chunks ahead through a 16-slot VGPR ring (was read-wait-use per chunk); arithmetic order unchanged
# speedup vs baseline: 1.0923x; 1.0041x over previous
.LBB0_582:
	v_mov_b32_e32 v49, v18
	v_add_u32_e32 v18, 8, v49
	v_readlane_b32 s8, v254, 18
	s_waitcnt vmcnt(0)
	v_lshlrev_b32_e32 v8, 16, v30
	v_and_b32_e32 v9, 0xffff0000, v30
	v_cmp_gt_i32_e32 vcc, s8, v18
	v_add_f32_e32 v12, 0, v8
	v_lshlrev_b32_e32 v10, 16, v31
	v_cndmask_b32_e32 v0, v49, v18, vcc
	v_ashrrev_i32_e32 v1, 31, v0
	v_lshlrev_b64 v[0:1], 11, v[0:1]
	v_lshl_add_u64 v[0:1], v[20:21], 0, v[0:1]
	v_and_b32_e32 v11, 0xffff0000, v31
	v_lshlrev_b32_e32 v42, 16, v28
	v_and_b32_e32 v43, 0xffff0000, v28
	v_lshlrev_b32_e32 v44, 16, v29
	v_and_b32_e32 v45, 0xffff0000, v29
	v_lshlrev_b32_e32 v58, 16, v26
	v_and_b32_e32 v59, 0xffff0000, v26
	v_lshlrev_b32_e32 v61, 16, v27
	v_and_b32_e32 v60, 0xffff0000, v27
	v_lshlrev_b32_e32 v63, 16, v24
	v_and_b32_e32 v62, 0xffff0000, v24
	v_lshlrev_b32_e32 v65, 16, v25
	v_and_b32_e32 v64, 0xffff0000, v25
	global_load_dwordx2 v[30:31], v[0:1], off
	global_load_dwordx2 v[28:29], v[0:1], off offset:512
	global_load_dwordx2 v[26:27], v[0:1], off offset:1024
	global_load_dwordx2 v[24:25], v[0:1], off offset:1536
	s_nop 0
	global_load_dwordx4 v[0:3], v[32:33], off
	global_load_dwordx4 v[4:7], v[34:35], off
	v_add_f32_e32 v12, v12, v9
	v_add_f32_e32 v12, v12, v10
	v_add_f32_e32 v46, v12, v11
	global_load_dwordx4 v[12:15], v[32:33], off offset:1024
	global_load_dwordx4 v[38:41], v[34:35], off offset:1024
	global_load_dwordx4 v[50:53], v[32:33], off offset:2048
	global_load_dwordx4 v[54:57], v[34:35], off offset:2048
	v_add_f32_e32 v46, v46, v42
	v_add_f32_e32 v46, v46, v43
	v_add_f32_e32 v46, v46, v44
	v_add_f32_e32 v46, v46, v45
	v_add_f32_e32 v46, v46, v58
	v_add_f32_e32 v46, v46, v59
	v_add_f32_e32 v46, v46, v61
	v_add_f32_e32 v46, v46, v60
	v_add_f32_e32 v46, v46, v63
	v_add_f32_e32 v46, v46, v62
	v_add_f32_e32 v46, v46, v65
	v_add_f32_e32 v46, v46, v64
	v_cmp_le_i32_e64 s[52:53], s8, v18
	s_mov_b32 s25, 1
	v_add_f32_dpp v46, v46, v46 quad_perm:[1,0,3,2] row_mask:0xf bank_mask:0xf bound_ctrl:1
	s_mov_b32 s26, 0
	s_mov_b32 s27, 0xf149f2ca
	v_add_f32_dpp v46, v46, v46 quad_perm:[2,3,0,1] row_mask:0xf bank_mask:0xf bound_ctrl:1
	s_nop 1
	v_add_f32_dpp v46, v46, v46 row_half_mirror row_mask:0xf bank_mask:0xf bound_ctrl:1
	s_nop 1
	v_add_f32_dpp v46, v46, v46 row_mirror row_mask:0xf bank_mask:0xf bound_ctrl:1
	s_nop 0
	v_readlane_b32 s10, v46, 16
	v_readlane_b32 s11, v46, 48
	v_readlane_b32 s8, v46, 0
	v_readlane_b32 s9, v46, 32
	v_mov_b32_e32 v66, s10
	v_mov_b32_e32 v67, s11
	v_pk_add_f32 v[66:67], s[8:9], v[66:67]
	s_nop 0
	v_add_f32_e32 v46, v66, v67
	v_mul_f32_e32 v46, 0x3a800000, v46
	v_pk_add_f32 v[8:9], v[8:9], v[46:47] op_sel_hi:[1,0] neg_lo:[0,1] neg_hi:[0,1]
	v_pk_add_f32 v[10:11], v[10:11], v[46:47] op_sel_hi:[1,0] neg_lo:[0,1] neg_hi:[0,1]
	v_pk_mul_f32 v[66:67], v[8:9], v[8:9]
	v_pk_mul_f32 v[68:69], v[10:11], v[10:11]
	v_pk_add_f32 v[70:71], v[42:43], v[46:47] op_sel_hi:[1,0] neg_lo:[0,1] neg_hi:[0,1]
	v_pk_add_f32 v[74:75], v[44:45], v[46:47] op_sel_hi:[1,0] neg_lo:[0,1] neg_hi:[0,1]
	v_pk_add_f32 v[58:59], v[58:59], v[46:47] op_sel_hi:[1,0] neg_lo:[0,1] neg_hi:[0,1]
	v_pk_add_f32 v[60:61], v[60:61], v[46:47] op_sel_hi:[1,0] neg_lo:[0,1] neg_hi:[0,1]
	v_pk_add_f32 v[42:43], v[62:63], v[46:47] op_sel_hi:[1,0] neg_lo:[0,1] neg_hi:[0,1]
	v_pk_add_f32 v[44:45], v[64:65], v[46:47] op_sel_hi:[1,0] neg_lo:[0,1] neg_hi:[0,1]
	v_add_f32_e32 v46, v66, v67
	v_add_f32_e32 v46, v68, v46
	v_pk_mul_f32 v[72:73], v[70:71], v[70:71]
	v_add_f32_e32 v46, v69, v46
	v_add_f32_e32 v46, v72, v46
	v_pk_mul_f32 v[76:77], v[74:75], v[74:75]
	v_add_f32_e32 v46, v73, v46
	v_add_f32_e32 v46, v76, v46
	v_pk_mul_f32 v[78:79], v[58:59], v[58:59]
	v_add_f32_e32 v46, v77, v46
	v_add_f32_e32 v46, v78, v46
	v_pk_mul_f32 v[80:81], v[60:61], v[60:61]
	v_add_f32_e32 v46, v79, v46
	v_add_f32_e32 v46, v81, v46
	v_pk_mul_f32 v[62:63], v[42:43], v[42:43]
	v_add_f32_e32 v46, v80, v46
	v_add_f32_e32 v46, v63, v46
	v_pk_mul_f32 v[64:65], v[44:45], v[44:45]
	v_add_f32_e32 v46, v62, v46
	v_add_f32_e32 v46, v65, v46
	v_add_f32_e32 v46, v64, v46
	s_nop 1
	v_add_f32_dpp v46, v46, v46 quad_perm:[1,0,3,2] row_mask:0xf bank_mask:0xf bound_ctrl:1
	s_nop 1
	v_add_f32_dpp v46, v46, v46 quad_perm:[2,3,0,1] row_mask:0xf bank_mask:0xf bound_ctrl:1
	s_nop 1
	v_add_f32_dpp v46, v46, v46 row_half_mirror row_mask:0xf bank_mask:0xf bound_ctrl:1
	s_nop 1
	v_add_f32_dpp v46, v46, v46 row_mirror row_mask:0xf bank_mask:0xf bound_ctrl:1
	s_nop 0
	v_readlane_b32 s10, v46, 16
	v_readlane_b32 s11, v46, 48
	v_readlane_b32 s8, v46, 0
	v_readlane_b32 s9, v46, 32
	v_mov_b32_e32 v62, s10
	v_mov_b32_e32 v63, s11
	v_pk_add_f32 v[62:63], s[8:9], v[62:63]
	s_mov_b32 s8, 0x800000
	v_add_f32_e32 v46, v62, v63
	v_fmamk_f32 v46, v46, 0x3a800000, v194
	v_cmp_gt_f32_e32 vcc, s8, v46
	v_mul_f32_e32 v62, 0x4b800000, v46
	s_mov_b32 s8, 0xfa000000
	v_cndmask_b32_e32 v46, v46, v62, vcc
	v_rsq_f32_e32 v46, v46
	s_nop 0
	v_mul_f32_e32 v62, 0x45800000, v46
	v_cndmask_b32_e32 v46, v46, v62, vcc
	v_pk_mul_f32 v[8:9], v[8:9], v[46:47] op_sel_hi:[1,0]
	v_pk_mul_f32 v[42:43], v[42:43], v[46:47] op_sel_hi:[1,0]
	s_waitcnt vmcnt(4)
	v_pk_fma_f32 v[8:9], v[0:1], v[8:9], v[4:5]
	v_pk_mul_f32 v[0:1], v[10:11], v[46:47] op_sel_hi:[1,0]
	s_nop 0
	v_pk_fma_f32 v[10:11], v[2:3], v[0:1], v[6:7]
	v_pk_mul_f32 v[0:1], v[70:71], v[46:47] op_sel_hi:[1,0]
	s_waitcnt vmcnt(2)
	v_pk_fma_f32 v[38:39], v[12:13], v[0:1], v[38:39]
	v_pk_mul_f32 v[0:1], v[74:75], v[46:47] op_sel_hi:[1,0]
	s_nop 0
	v_pk_fma_f32 v[40:41], v[14:15], v[0:1], v[40:41]
	v_pk_mul_f32 v[0:1], v[58:59], v[46:47] op_sel_hi:[1,0]
	s_waitcnt vmcnt(0)
	v_pk_fma_f32 v[12:13], v[50:51], v[0:1], v[54:55]
	v_pk_mul_f32 v[0:1], v[60:61], v[46:47] op_sel_hi:[1,0]
	s_nop 0
	v_pk_fma_f32 v[14:15], v[52:53], v[0:1], v[56:57] op_sel:[0,1,0] op_sel_hi:[1,0,1]
	global_load_dwordx4 v[0:3], v[32:33], off offset:3072
	global_load_dwordx4 v[4:7], v[34:35], off offset:3072
	s_waitcnt vmcnt(0)
	v_pk_fma_f32 v[50:51], v[0:1], v[42:43], v[4:5] op_sel:[0,1,0] op_sel_hi:[1,0,1]
	v_pk_mul_f32 v[0:1], v[44:45], v[46:47] op_sel_hi:[1,0]
	s_nop 0
	v_pk_fma_f32 v[52:53], v[2:3], v[0:1], v[6:7] op_sel:[0,1,0] op_sel_hi:[1,0,1]
	v_add_co_u32_e32 v2, vcc, s8, v36
	v_cvt_pk_bf16_f32 v0, v8, v9
	v_cvt_pk_bf16_f32 v1, v10, v11
	v_addc_co_u32_e32 v3, vcc, -1, v37, vcc
	global_store_dwordx2 v[2:3], v[0:1], off offset:-1540
	v_cvt_pk_bf16_f32 v0, v38, v39
	v_cvt_pk_bf16_f32 v1, v40, v41
	global_store_dwordx2 v[2:3], v[0:1], off offset:-1028
	v_cvt_pk_bf16_f32 v0, v12, v13
	v_cvt_pk_bf16_f32 v1, v14, v15
	global_store_dwordx2 v[2:3], v[0:1], off offset:-516
	v_cvt_pk_bf16_f32 v0, v50, v51
	v_cvt_pk_bf16_f32 v1, v52, v53
	global_store_dwordx2 v[2:3], v[0:1], off offset:-4
	v_min_i32_e32 v0, 0x2000, v49
	v_ashrrev_i32_e32 v0, 11, v0
	v_mul_hi_i32_i24_e32 v1, 0x6000, v0
	v_mul_i32_i24_e32 v0, 0x6000, v0
	v_lshl_add_u64 v[0:1], s[4:5], 0, v[0:1]
	v_lshl_add_u64 v[0:1], v[0:1], 0, v[192:193]
	s_mov_b64 s[8:9], 0x3000
	v_lshl_add_u64 v[42:43], v[0:1], 0, s[8:9]
	s_movk_i32 s8, 0x4000
	v_add_co_u32_e32 v4, vcc, s8, v0
	v_lshl_add_u64 v[44:45], v[0:1], 0, s[12:13]
	s_nop 0
	v_addc_co_u32_e32 v5, vcc, 0, v1, vcc
	global_load_dwordx4 v[0:3], v[4:5], off offset:-4096
	s_nop 0
	global_load_dwordx4 v[4:7], v[4:5], off
	s_waitcnt vmcnt(0)
	v_pk_add_f32 v[4:5], v[4:5], 1.0 op_sel_hi:[1,0]
	s_nop 0
	v_pk_fma_f32 v[8:9], v[8:9], v[4:5], v[0:1]
	v_pk_add_f32 v[0:1], v[6:7], 1.0 op_sel_hi:[1,0]
	s_nop 0
	v_pk_fma_f32 v[10:11], v[10:11], v[0:1], v[2:3]
	global_load_dwordx4 v[0:3], v[42:43], off offset:1024
	global_load_dwordx4 v[4:7], v[44:45], off offset:1024
	s_waitcnt vmcnt(0)
	v_pk_add_f32 v[4:5], v[4:5], 1.0 op_sel_hi:[1,0]
	s_nop 0
	v_pk_fma_f32 v[0:1], v[38:39], v[4:5], v[0:1]
	v_pk_add_f32 v[4:5], v[6:7], 1.0 op_sel_hi:[1,0]
	s_nop 0
	v_pk_fma_f32 v[2:3], v[40:41], v[4:5], v[2:3]
	global_load_dwordx4 v[4:7], v[42:43], off offset:2048
	global_load_dwordx4 v[38:41], v[44:45], off offset:2048
	s_waitcnt vmcnt(0)
	v_pk_add_f32 v[38:39], v[38:39], 1.0 op_sel_hi:[1,0]
	s_nop 0
	v_pk_fma_f32 v[4:5], v[12:13], v[38:39], v[4:5]
	v_pk_add_f32 v[12:13], v[40:41], 1.0 op_sel_hi:[1,0]
	global_load_dwordx4 v[38:41], v[42:43], off offset:3072
	s_nop 0
	global_load_dwordx4 v[42:45], v[44:45], off offset:3072
	v_pk_fma_f32 v[6:7], v[14:15], v[12:13], v[6:7]
	s_waitcnt vmcnt(0)
	v_pk_add_f32 v[12:13], v[42:43], 1.0 op_sel_hi:[1,0]
	s_nop 0
	v_pk_fma_f32 v[14:15], v[50:51], v[12:13], v[38:39]
	v_cvt_pk_bf16_f32 v38, v8, v9
	v_cvt_pk_bf16_f32 v39, v10, v11
	v_pk_add_f32 v[12:13], v[44:45], 1.0 op_sel_hi:[1,0]
	global_store_dwordx2 v[36:37], v[38:39], off offset:-1540
	v_cvt_pk_bf16_f32 v38, v0, v1
	v_cvt_pk_bf16_f32 v39, v2, v3
	v_pk_fma_f32 v[12:13], v[52:53], v[12:13], v[40:41]
	global_store_dwordx2 v[36:37], v[38:39], off offset:-1028
	v_cvt_pk_bf16_f32 v38, v4, v5
	v_cvt_pk_bf16_f32 v39, v6, v7
	global_store_dwordx2 v[36:37], v[38:39], off offset:-516
	v_cvt_pk_bf16_f32 v38, v14, v15
	v_cvt_pk_bf16_f32 v39, v12, v13
	global_store_dwordx2 v[36:37], v[38:39], off offset:-4
	ds_read_b128 v[88:91], v22
	ds_read_b128 v[96:99], v22 offset:1024
	ds_read_b128 v[100:103], v22 offset:2048
	ds_read_b128 v[104:107], v22 offset:3072
	ds_read_b128 v[108:111], v22 offset:4096
	ds_read_b128 v[112:115], v22 offset:5120
	ds_read_b128 v[116:119], v22 offset:6144
	ds_read_b128 v[120:123], v22 offset:7168
	ds_read_b128 v[124:127], v22 offset:8192
	ds_read_b128 v[152:155], v22 offset:20480
	s_waitcnt lgkmcnt(9)
	v_mul_f32_e32 v89, v9, v89
	v_fmac_f32_e32 v89, v8, v88
	v_fmac_f32_e32 v89, v10, v90
	v_fmac_f32_e32 v89, v11, v91
	v_add_f32_e32 v42, 0, v89
	ds_read_b128 v[128:131], v22 offset:9216
	s_waitcnt lgkmcnt(9)
	v_mul_f32_e32 v97, v1, v97
	v_fmac_f32_e32 v97, v0, v96
	v_fmac_f32_e32 v97, v2, v98
	v_fmac_f32_e32 v97, v3, v99
	v_add_f32_e32 v42, v42, v97
	ds_read_b128 v[132:135], v22 offset:10240
	s_waitcnt lgkmcnt(9)
	v_mul_f32_e32 v101, v5, v101
	v_fmac_f32_e32 v101, v4, v100
	v_fmac_f32_e32 v101, v6, v102
	v_fmac_f32_e32 v101, v7, v103
	v_add_f32_e32 v42, v42, v101
	ds_read_b128 v[136:139], v22 offset:11264
	s_waitcnt lgkmcnt(9)
	v_mul_f32_e32 v105, v15, v105
	v_fmac_f32_e32 v105, v14, v104
	v_fmac_f32_e32 v105, v12, v106
	v_fmac_f32_e32 v105, v13, v107
	v_add_f32_e32 v38, v42, v105
	ds_read_b128 v[140:143], v22 offset:12288
	s_waitcnt lgkmcnt(9)
	v_mul_f32_e32 v39, v9, v109
	v_fmac_f32_e32 v39, v8, v108
	v_fmac_f32_e32 v39, v10, v110
	v_fmac_f32_e32 v39, v11, v111
	ds_read_b128 v[144:147], v22 offset:13312
	v_add_f32_e32 v39, 0, v39
	s_waitcnt lgkmcnt(9)
	v_mul_f32_e32 v113, v1, v113
	v_fmac_f32_e32 v113, v0, v112
	v_fmac_f32_e32 v113, v2, v114
	v_fmac_f32_e32 v113, v3, v115
	v_add_f32_e32 v39, v39, v113
	ds_read_b128 v[148:151], v22 offset:14336
	s_waitcnt lgkmcnt(9)
	v_mul_f32_e32 v117, v5, v117
	v_fmac_f32_e32 v117, v4, v116
	v_fmac_f32_e32 v117, v6, v118
	v_fmac_f32_e32 v117, v7, v119
	v_add_f32_e32 v39, v39, v117
	ds_read_b128 v[88:91], v22 offset:15360
	s_waitcnt lgkmcnt(9)
	v_mul_f32_e32 v121, v15, v121
	v_fmac_f32_e32 v121, v14, v120
	v_fmac_f32_e32 v121, v12, v122
	v_fmac_f32_e32 v121, v13, v123
	v_add_f32_e32 v39, v39, v121
	ds_read_b128 v[92:95], v22 offset:16384
	s_waitcnt lgkmcnt(9)
	v_mul_f32_e32 v125, v9, v125
	v_fmac_f32_e32 v125, v8, v124
	v_fmac_f32_e32 v125, v10, v126
	v_fmac_f32_e32 v125, v11, v127
	v_add_f32_e32 v44, 0, v125
	ds_read_b128 v[96:99], v22 offset:17408
	s_waitcnt lgkmcnt(8)
	v_mul_f32_e32 v129, v1, v129
	v_fmac_f32_e32 v129, v0, v128
	v_fmac_f32_e32 v129, v2, v130
	v_fmac_f32_e32 v129, v3, v131
	v_add_f32_e32 v44, v44, v129
	ds_read_b128 v[100:103], v22 offset:18432
	s_waitcnt lgkmcnt(8)
	v_mul_f32_e32 v133, v5, v133
	v_fmac_f32_e32 v133, v4, v132
	v_fmac_f32_e32 v133, v6, v134
	v_fmac_f32_e32 v133, v7, v135
	v_add_f32_e32 v44, v44, v133
	s_waitcnt lgkmcnt(7)
	v_mul_f32_e32 v137, v15, v137
	v_fmac_f32_e32 v137, v14, v136
	v_fmac_f32_e32 v137, v12, v138
	v_fmac_f32_e32 v137, v13, v139
	v_add_f32_e32 v40, v44, v137
	ds_read_b128 v[108:111], v22 offset:21504
	s_waitcnt lgkmcnt(7)
	v_mul_f32_e32 v41, v9, v141
	v_fmac_f32_e32 v41, v8, v140
	v_fmac_f32_e32 v41, v10, v142
	v_fmac_f32_e32 v41, v11, v143
	ds_read_b128 v[112:115], v22 offset:22528
	v_add_f32_e32 v41, 0, v41
	s_waitcnt lgkmcnt(7)
	v_mul_f32_e32 v145, v1, v145
	v_fmac_f32_e32 v145, v0, v144
	v_fmac_f32_e32 v145, v2, v146
	v_fmac_f32_e32 v145, v3, v147
	v_add_f32_e32 v41, v41, v145
	ds_read_b128 v[116:119], v22 offset:23552
	s_waitcnt lgkmcnt(7)
	v_mul_f32_e32 v149, v5, v149
	v_fmac_f32_e32 v149, v4, v148
	v_fmac_f32_e32 v149, v6, v150
	v_fmac_f32_e32 v149, v7, v151
	v_add_f32_e32 v41, v41, v149
	ds_read_b128 v[120:123], v22 offset:24576
	s_waitcnt lgkmcnt(7)
	v_mul_f32_e32 v89, v15, v89
	v_fmac_f32_e32 v89, v14, v88
	v_fmac_f32_e32 v89, v12, v90
	v_fmac_f32_e32 v89, v13, v91
	v_add_f32_e32 v41, v41, v89
	ds_read_b128 v[124:127], v22 offset:25600
	s_waitcnt lgkmcnt(7)
	v_mul_f32_e32 v93, v9, v93
	v_fmac_f32_e32 v93, v8, v92
	v_fmac_f32_e32 v93, v10, v94
	v_fmac_f32_e32 v93, v11, v95
	v_add_f32_e32 v46, 0, v93
	ds_read_b128 v[128:131], v22 offset:26624
	s_waitcnt lgkmcnt(7)
	v_mul_f32_e32 v97, v1, v97
	v_fmac_f32_e32 v97, v0, v96
	v_fmac_f32_e32 v97, v2, v98
	v_fmac_f32_e32 v97, v3, v99
	v_add_f32_e32 v46, v46, v97
	ds_read_b128 v[132:135], v22 offset:27648
	s_waitcnt lgkmcnt(7)
	v_mul_f32_e32 v101, v5, v101
	v_fmac_f32_e32 v101, v4, v100
	v_fmac_f32_e32 v101, v6, v102
	v_fmac_f32_e32 v101, v7, v103
	v_add_f32_e32 v46, v46, v101
	ds_read_b128 v[136:139], v22 offset:28672
	ds_read_b128 v[156:159], v22 offset:19456
	s_waitcnt lgkmcnt(0)
	v_mul_f32_e32 v157, v15, v157
	v_fmac_f32_e32 v157, v14, v156
	v_fmac_f32_e32 v157, v12, v158
	v_fmac_f32_e32 v157, v13, v159
	v_add_f32_e32 v42, v46, v157
	v_mul_f32_e32 v43, v9, v153
	v_fmac_f32_e32 v43, v8, v152
	v_fmac_f32_e32 v43, v10, v154
	v_fmac_f32_e32 v43, v11, v155
	ds_read_b128 v[140:143], v22 offset:29696
	v_add_f32_e32 v43, 0, v43
	v_mul_f32_e32 v158, v1, v109
	v_fmac_f32_e32 v158, v0, v108
	v_fmac_f32_e32 v158, v2, v110
	v_fmac_f32_e32 v158, v3, v111
	ds_read_b128 v[144:147], v22 offset:30720
	v_add_f32_e32 v43, v43, v158
	v_mul_f32_e32 v44, v5, v113
	v_fmac_f32_e32 v44, v4, v112
	v_fmac_f32_e32 v44, v6, v114
	v_fmac_f32_e32 v44, v7, v115
	ds_read_b128 v[148:151], v22 offset:31744
	v_add_f32_e32 v43, v43, v44
	v_mul_f32_e32 v44, v15, v117
	v_fmac_f32_e32 v44, v14, v116
	v_fmac_f32_e32 v44, v12, v118
	v_fmac_f32_e32 v44, v13, v119
	ds_read_b128 v[88:91], v22 offset:32768
	v_add_f32_e32 v43, v43, v44
	v_mul_f32_e32 v44, v9, v121
	v_fmac_f32_e32 v44, v8, v120
	v_fmac_f32_e32 v44, v10, v122
	v_fmac_f32_e32 v44, v11, v123
	ds_read_b128 v[92:95], v22 offset:33792
	v_add_f32_e32 v44, 0, v44
	v_mul_f32_e32 v159, v1, v125
	v_fmac_f32_e32 v159, v0, v124
	v_fmac_f32_e32 v159, v2, v126
	v_fmac_f32_e32 v159, v3, v127
	ds_read_b128 v[96:99], v22 offset:34816
	v_add_f32_e32 v44, v44, v159
	v_mul_f32_e32 v45, v5, v129
	v_fmac_f32_e32 v45, v4, v128
	v_fmac_f32_e32 v45, v6, v130
	v_fmac_f32_e32 v45, v7, v131
	ds_read_b128 v[100:103], v22 offset:35840
	v_add_f32_e32 v44, v44, v45
	v_mul_f32_e32 v45, v15, v133
	v_fmac_f32_e32 v45, v14, v132
	v_fmac_f32_e32 v45, v12, v134
	v_fmac_f32_e32 v45, v13, v135
	ds_read_b128 v[104:107], v22 offset:36864
	v_add_f32_e32 v44, v44, v45
	v_mul_f32_e32 v45, v9, v137
	v_fmac_f32_e32 v45, v8, v136
	v_fmac_f32_e32 v45, v10, v138
	v_fmac_f32_e32 v45, v11, v139
	ds_read_b128 v[108:111], v22 offset:37888
	v_add_f32_e32 v45, 0, v45
	s_waitcnt lgkmcnt(8)
	v_mul_f32_e32 v46, v1, v141
	v_fmac_f32_e32 v46, v0, v140
	v_fmac_f32_e32 v46, v2, v142
	v_fmac_f32_e32 v46, v3, v143
	ds_read_b128 v[112:115], v22 offset:38912
	v_add_f32_e32 v45, v45, v46
	s_waitcnt lgkmcnt(8)
	v_mul_f32_e32 v46, v5, v145
	v_fmac_f32_e32 v46, v4, v144
	v_fmac_f32_e32 v46, v6, v146
	v_fmac_f32_e32 v46, v7, v147
	ds_read_b128 v[116:119], v22 offset:39936
	v_add_f32_e32 v45, v45, v46
	s_waitcnt lgkmcnt(8)
	v_mul_f32_e32 v46, v15, v149
	v_fmac_f32_e32 v46, v14, v148
	v_fmac_f32_e32 v46, v12, v150
	v_fmac_f32_e32 v46, v13, v151
	ds_read_b128 v[120:123], v22 offset:40960
	v_add_f32_e32 v45, v45, v46
	s_waitcnt lgkmcnt(8)
	v_mul_f32_e32 v46, v9, v89
	v_fmac_f32_e32 v46, v8, v88
	v_fmac_f32_e32 v46, v10, v90
	v_fmac_f32_e32 v46, v11, v91
	ds_read_b128 v[124:127], v22 offset:41984
	v_add_f32_e32 v46, 0, v46
	s_waitcnt lgkmcnt(8)
	v_mul_f32_e32 v49, v1, v93
	v_fmac_f32_e32 v49, v0, v92
	v_fmac_f32_e32 v49, v2, v94
	v_fmac_f32_e32 v49, v3, v95
	ds_read_b128 v[128:131], v22 offset:43008
	v_add_f32_e32 v46, v46, v49
	s_waitcnt lgkmcnt(8)
	v_mul_f32_e32 v49, v5, v97
	v_fmac_f32_e32 v49, v4, v96
	v_fmac_f32_e32 v49, v6, v98
	v_fmac_f32_e32 v49, v7, v99
	ds_read_b128 v[132:135], v22 offset:44032
	v_add_f32_e32 v46, v46, v49
	s_waitcnt lgkmcnt(8)
	v_mul_f32_e32 v49, v15, v101
	v_fmac_f32_e32 v49, v14, v100
	v_fmac_f32_e32 v49, v12, v102
	v_fmac_f32_e32 v49, v13, v103
	ds_read_b128 v[136:139], v22 offset:45056
	v_add_f32_e32 v46, v46, v49
	s_waitcnt lgkmcnt(8)
	v_mul_f32_e32 v49, v9, v105
	v_fmac_f32_e32 v49, v8, v104
	v_fmac_f32_e32 v49, v10, v106
	v_fmac_f32_e32 v49, v11, v107
	ds_read_b128 v[140:143], v22 offset:46080
	v_add_f32_e32 v49, 0, v49
	s_waitcnt lgkmcnt(8)
	v_mul_f32_e32 v109, v1, v109
	v_fmac_f32_e32 v109, v0, v108
	v_fmac_f32_e32 v109, v2, v110
	v_fmac_f32_e32 v109, v3, v111
	v_add_f32_e32 v49, v49, v109
	ds_read_b128 v[144:147], v22 offset:47104
	s_waitcnt lgkmcnt(8)
	v_mul_f32_e32 v113, v5, v113
	v_fmac_f32_e32 v113, v4, v112
	v_fmac_f32_e32 v113, v6, v114
	v_fmac_f32_e32 v113, v7, v115
	v_add_f32_e32 v49, v49, v113
	ds_read_b128 v[148:151], v22 offset:48128
	s_waitcnt lgkmcnt(8)
	v_mul_f32_e32 v117, v15, v117
	v_fmac_f32_e32 v117, v14, v116
	v_fmac_f32_e32 v117, v12, v118
	v_fmac_f32_e32 v117, v13, v119
	v_add_f32_e32 v49, v49, v117
	ds_read_b128 v[88:91], v22 offset:49152
	s_waitcnt lgkmcnt(8)
	v_mul_f32_e32 v121, v9, v121
	v_fmac_f32_e32 v121, v8, v120
	v_fmac_f32_e32 v121, v10, v122
	v_fmac_f32_e32 v121, v11, v123
	v_add_f32_e32 v54, 0, v121
	ds_read_b128 v[92:95], v22 offset:50176
	s_waitcnt lgkmcnt(8)
	v_mul_f32_e32 v125, v1, v125
	v_fmac_f32_e32 v125, v0, v124
	v_fmac_f32_e32 v125, v2, v126
	v_fmac_f32_e32 v125, v3, v127
	v_add_f32_e32 v54, v54, v125
	ds_read_b128 v[96:99], v22 offset:51200
	s_waitcnt lgkmcnt(8)
	v_mul_f32_e32 v129, v5, v129
	v_fmac_f32_e32 v129, v4, v128
	v_fmac_f32_e32 v129, v6, v130
	v_fmac_f32_e32 v129, v7, v131
	v_add_f32_e32 v54, v54, v129
	ds_read_b128 v[100:103], v22 offset:52224
	s_waitcnt lgkmcnt(8)
	v_mul_f32_e32 v133, v15, v133
	v_fmac_f32_e32 v133, v14, v132
	v_fmac_f32_e32 v133, v12, v134
	v_fmac_f32_e32 v133, v13, v135
	v_add_f32_e32 v50, v54, v133
	ds_read_b128 v[104:107], v22 offset:53248
	s_waitcnt lgkmcnt(8)
	v_mul_f32_e32 v51, v9, v137
	v_fmac_f32_e32 v51, v8, v136
	v_fmac_f32_e32 v51, v10, v138
	v_fmac_f32_e32 v51, v11, v139
	ds_read_b128 v[108:111], v22 offset:54272
	v_add_f32_e32 v51, 0, v51
	s_waitcnt lgkmcnt(8)
	v_mul_f32_e32 v141, v1, v141
	v_fmac_f32_e32 v141, v0, v140
	v_fmac_f32_e32 v141, v2, v142
	v_fmac_f32_e32 v141, v3, v143
	v_add_f32_e32 v51, v51, v141
	ds_read_b128 v[112:115], v22 offset:55296
	s_waitcnt lgkmcnt(8)
	v_mul_f32_e32 v145, v5, v145
	v_fmac_f32_e32 v145, v4, v144
	v_fmac_f32_e32 v145, v6, v146
	v_fmac_f32_e32 v145, v7, v147
	v_add_f32_e32 v51, v51, v145
	ds_read_b128 v[116:119], v22 offset:56320
	s_waitcnt lgkmcnt(8)
	v_mul_f32_e32 v149, v15, v149
	v_fmac_f32_e32 v149, v14, v148
	v_fmac_f32_e32 v149, v12, v150
	v_fmac_f32_e32 v149, v13, v151
	v_add_f32_e32 v51, v51, v149
	ds_read_b128 v[120:123], v22 offset:57344
	s_waitcnt lgkmcnt(8)
	v_mul_f32_e32 v89, v9, v89
	v_fmac_f32_e32 v89, v8, v88
	v_fmac_f32_e32 v89, v10, v90
	v_fmac_f32_e32 v89, v11, v91
	v_add_f32_e32 v56, 0, v89
	ds_read_b128 v[124:127], v22 offset:58368
	s_waitcnt lgkmcnt(8)
	v_mul_f32_e32 v93, v1, v93
	v_fmac_f32_e32 v93, v0, v92
	v_fmac_f32_e32 v93, v2, v94
	v_fmac_f32_e32 v93, v3, v95
	v_add_f32_e32 v56, v56, v93
	ds_read_b128 v[128:131], v22 offset:59392
	s_waitcnt lgkmcnt(8)
	v_mul_f32_e32 v97, v5, v97
	v_fmac_f32_e32 v97, v4, v96
	v_fmac_f32_e32 v97, v6, v98
	v_fmac_f32_e32 v97, v7, v99
	v_add_f32_e32 v56, v56, v97
	ds_read_b128 v[132:135], v22 offset:60416
	s_waitcnt lgkmcnt(8)
	v_mul_f32_e32 v101, v15, v101
	v_fmac_f32_e32 v101, v14, v100
	v_fmac_f32_e32 v101, v12, v102
	v_fmac_f32_e32 v101, v13, v103
	v_add_f32_e32 v52, v56, v101
	ds_read_b128 v[136:139], v22 offset:61440
	s_waitcnt lgkmcnt(8)
	v_mul_f32_e32 v53, v9, v105
	v_fmac_f32_e32 v53, v8, v104
	v_fmac_f32_e32 v53, v10, v106
	v_fmac_f32_e32 v53, v11, v107
	ds_read_b128 v[140:143], v22 offset:62464
	v_add_f32_e32 v53, 0, v53
	s_waitcnt lgkmcnt(8)
	v_mul_f32_e32 v109, v1, v109
	v_fmac_f32_e32 v109, v0, v108
	v_fmac_f32_e32 v109, v2, v110
	v_fmac_f32_e32 v109, v3, v111
	v_add_f32_e32 v53, v53, v109
	ds_read_b128 v[144:147], v22 offset:63488
	s_waitcnt lgkmcnt(8)
	v_mul_f32_e32 v113, v5, v113
	v_fmac_f32_e32 v113, v4, v112
	v_fmac_f32_e32 v113, v6, v114
	v_fmac_f32_e32 v113, v7, v115
	v_add_f32_e32 v53, v53, v113
	ds_read_b128 v[148:151], v22 offset:64512
	s_waitcnt lgkmcnt(8)
	v_mul_f32_e32 v117, v15, v117
	v_fmac_f32_e32 v117, v14, v116
	v_fmac_f32_e32 v117, v12, v118
	v_fmac_f32_e32 v117, v13, v119
	v_add_f32_e32 v53, v53, v117
	s_waitcnt lgkmcnt(7)
	v_mul_f32_e32 v121, v9, v121
	v_fmac_f32_e32 v121, v8, v120
	v_fmac_f32_e32 v121, v10, v122
	v_fmac_f32_e32 v121, v11, v123
	v_add_f32_e32 v58, 0, v121
	s_waitcnt lgkmcnt(6)
	v_mul_f32_e32 v125, v1, v125
	v_fmac_f32_e32 v125, v0, v124
	v_fmac_f32_e32 v125, v2, v126
	v_fmac_f32_e32 v125, v3, v127
	v_add_f32_e32 v58, v58, v125
	s_waitcnt lgkmcnt(5)
	v_mul_f32_e32 v129, v5, v129
	v_fmac_f32_e32 v129, v4, v128
	v_fmac_f32_e32 v129, v6, v130
	v_fmac_f32_e32 v129, v7, v131
	v_add_f32_e32 v58, v58, v129
	s_waitcnt lgkmcnt(4)
	v_mul_f32_e32 v133, v15, v133
	v_fmac_f32_e32 v133, v14, v132
	v_fmac_f32_e32 v133, v12, v134
	v_fmac_f32_e32 v133, v13, v135
	v_add_f32_e32 v58, v58, v133
	s_waitcnt lgkmcnt(3)
	v_mul_f32_e32 v9, v9, v137
	v_fmac_f32_e32 v9, v8, v136
	v_fmac_f32_e32 v9, v10, v138
	v_fmac_f32_e32 v9, v11, v139
	v_add_f32_e32 v54, 0, v9
	s_waitcnt lgkmcnt(2)
	v_mul_f32_e32 v1, v1, v141
	v_fmac_f32_e32 v1, v0, v140
	v_fmac_f32_e32 v1, v2, v142
	v_fmac_f32_e32 v1, v3, v143
	v_add_f32_e32 v8, v54, v1
	s_waitcnt lgkmcnt(1)
	v_mul_f32_e32 v145, v5, v145
	v_fmac_f32_e32 v145, v4, v144
	v_fmac_f32_e32 v145, v6, v146
	v_fmac_f32_e32 v145, v7, v147
	v_add_f32_e32 v4, v8, v145
	v_cndmask_b32_e64 v5, v51, v41, s[42:43]
	v_cndmask_b32_e64 v6, v52, v42, s[42:43]
	v_cndmask_b32_e64 v7, v53, v43, s[42:43]
	v_cndmask_b32_e64 v8, v58, v44, s[42:43]
	s_waitcnt lgkmcnt(0)
	v_mul_f32_e32 v149, v15, v149
	v_fmac_f32_e32 v149, v14, v148
	v_fmac_f32_e32 v149, v12, v150
	v_fmac_f32_e32 v149, v13, v151
	v_add_f32_e32 v0, v4, v149
	v_cndmask_b32_e64 v1, v38, v46, s[42:43]
	v_cndmask_b32_e64 v2, v46, v38, s[42:43]
	v_cndmask_b32_e64 v3, v49, v39, s[42:43]
	v_cndmask_b32_e64 v4, v50, v40, s[42:43]
	v_add_f32_dpp v1, v1, v2 quad_perm:[1,0,3,2] row_mask:0xf bank_mask:0xf bound_ctrl:1
	v_cndmask_b32_e64 v2, v39, v49, s[42:43]
	s_nop 1
	v_add_f32_dpp v2, v2, v3 quad_perm:[1,0,3,2] row_mask:0xf bank_mask:0xf bound_ctrl:1
	v_cndmask_b32_e64 v3, v40, v50, s[42:43]
	s_nop 1
	v_add_f32_dpp v3, v3, v4 quad_perm:[1,0,3,2] row_mask:0xf bank_mask:0xf bound_ctrl:1
	v_cndmask_b32_e64 v4, v41, v51, s[42:43]
	s_nop 1
	v_add_f32_dpp v4, v4, v5 quad_perm:[1,0,3,2] row_mask:0xf bank_mask:0xf bound_ctrl:1
	v_cndmask_b32_e64 v5, v42, v52, s[42:43]
	s_nop 1
	v_add_f32_dpp v5, v5, v6 quad_perm:[1,0,3,2] row_mask:0xf bank_mask:0xf bound_ctrl:1
	v_cndmask_b32_e64 v6, v43, v53, s[42:43]
	s_nop 1
	v_add_f32_dpp v6, v6, v7 quad_perm:[1,0,3,2] row_mask:0xf bank_mask:0xf bound_ctrl:1
	v_cndmask_b32_e64 v7, v44, v58, s[42:43]
	s_nop 1
	v_add_f32_dpp v7, v7, v8 quad_perm:[1,0,3,2] row_mask:0xf bank_mask:0xf bound_ctrl:1
	v_cndmask_b32_e64 v8, v45, v0, s[42:43]
	v_cndmask_b32_e64 v0, v0, v45, s[42:43]
	s_nop 1
	v_add_f32_dpp v0, v8, v0 quad_perm:[1,0,3,2] row_mask:0xf bank_mask:0xf bound_ctrl:1
	v_cndmask_b32_e64 v8, v1, v5, s[44:45]
	v_cndmask_b32_e64 v1, v5, v1, s[44:45]
	v_cndmask_b32_e64 v5, v2, v6, s[44:45]
	v_cndmask_b32_e64 v2, v6, v2, s[44:45]
	v_add_f32_dpp v1, v8, v1 quad_perm:[2,3,0,1] row_mask:0xf bank_mask:0xf bound_ctrl:1
	s_nop 0
	v_add_f32_dpp v2, v5, v2 quad_perm:[2,3,0,1] row_mask:0xf bank_mask:0xf bound_ctrl:1
	v_cndmask_b32_e64 v5, v3, v7, s[44:45]
	v_cndmask_b32_e64 v3, v7, v3, s[44:45]
	s_nop 1
	v_add_f32_dpp v3, v5, v3 quad_perm:[2,3,0,1] row_mask:0xf bank_mask:0xf bound_ctrl:1
	v_cndmask_b32_e64 v5, v4, v0, s[44:45]
	v_cndmask_b32_e64 v0, v0, v4, s[44:45]
	v_cndmask_b32_e64 v4, v1, v3, s[46:47]
	v_cndmask_b32_e64 v1, v3, v1, s[46:47]
	ds_bpermute_b32 v3, v17, v4
	v_add_f32_dpp v0, v5, v0 quad_perm:[2,3,0,1] row_mask:0xf bank_mask:0xf bound_ctrl:1
	s_waitcnt lgkmcnt(0)
	v_add_f32_e32 v1, v1, v3
	v_cndmask_b32_e64 v3, v2, v0, s[46:47]
	v_cndmask_b32_e64 v0, v0, v2, s[46:47]
	ds_bpermute_b32 v2, v17, v3
	s_waitcnt lgkmcnt(0)
	v_add_f32_e32 v0, v0, v2
	v_cndmask_b32_e64 v2, v1, v0, s[48:49]
	v_cndmask_b32_e64 v0, v0, v1, s[48:49]
	ds_bpermute_b32 v1, v19, v2
	s_waitcnt lgkmcnt(0)
	v_add_f32_e32 v0, v0, v1
	ds_bpermute_b32 v1, v47, v0
	s_waitcnt lgkmcnt(0)
	v_add_f32_e32 v0, v0, v1
	ds_bpermute_b32 v1, v48, v0
	s_waitcnt lgkmcnt(0)
	v_add_f32_e32 v40, v0, v1
	s_nop 0
	v_readlane_b32 s8, v40, 0
	v_readlane_b32 s13, v40, 12
	v_readlane_b32 s24, v40, 2
	v_mul_f32_e32 v0, s8, v235
	v_exp_f32_e32 v0, v0
	v_readlane_b32 s23, v40, 10
	v_readlane_b32 s22, v40, 6
	v_readlane_b32 s20, v40, 14
	v_add_f32_e32 v0, 1.0, v0
	v_div_scale_f32 v1, s[8:9], v0, v0, 1.0
	v_rcp_f32_e32 v2, v1
	v_readlane_b32 s8, v254, 43
	v_readlane_b32 s10, v254, 45
	v_readlane_b32 s11, v254, 46
	v_fma_f32 v3, -v1, v2, 1.0
	v_fmac_f32_e32 v2, v3, v2
	v_div_scale_f32 v3, vcc, 1.0, v0, 1.0
	v_mul_f32_e32 v4, v3, v2
	v_fma_f32 v5, -v1, v4, v3
	v_fmac_f32_e32 v4, v5, v2
	v_fma_f32 v1, -v1, v4, v3
	v_div_fmas_f32 v1, v1, v2, v4
	v_div_fixup_f32 v41, v1, v0, 1.0
	global_load_dwordx4 v[0:3], v193, s[10:11] offset:48
	global_load_dwordx4 v[4:7], v193, s[10:11] offset:32
	global_load_dwordx4 v[8:11], v193, s[10:11] offset:16
	global_load_dwordx4 v[12:15], v193, s[10:11]
	v_readlane_b32 s8, v40, 8
	v_readlane_b32 s9, v254, 44
	v_readlane_b32 s19, v40, 1
	v_mul_f32_e32 v38, s8, v235
	v_exp_f32_e32 v38, v38
	v_readlane_b32 s18, v40, 9
	v_readlane_b32 s17, v40, 5
	v_readlane_b32 s16, v40, 13
	v_add_f32_e32 v38, 1.0, v38
	v_div_scale_f32 v39, s[8:9], v38, v38, 1.0
	v_rcp_f32_e32 v42, v39
	s_mov_b32 s9, 0xf149f2ca
	v_readlane_b32 s8, v40, 4
	v_readlane_b32 s15, v40, 3
	v_fma_f32 v43, -v39, v42, 1.0
	v_fmac_f32_e32 v42, v43, v42
	v_div_scale_f32 v43, vcc, 1.0, v38, 1.0
	v_mul_f32_e32 v44, v43, v42
	v_fma_f32 v45, -v39, v44, v43
	v_fmac_f32_e32 v44, v45, v42
	v_fma_f32 v39, -v39, v44, v43
	v_div_fmas_f32 v39, v39, v42, v44
	v_div_fixup_f32 v38, v39, v38, 1.0
	v_readlane_b32 s14, v40, 11
	v_readlane_b32 s12, v40, 7
	v_readlane_b32 s10, v40, 15
	s_waitcnt vmcnt(0)
	v_add_f32_e32 v12, v12, v41
	v_add_f32_e32 v39, v13, v38
	v_cmp_lt_f32_e32 vcc, s9, v12
	v_max_f32_e32 v40, 0xf149f2ca, v12
	s_nop 0
	v_cndmask_b32_e32 v12, 0, v41, vcc
	v_cmp_ngt_f32_e32 vcc, v39, v40
	s_cbranch_vccz .LBB0_586
	v_cmp_nlt_f32_e32 vcc, s9, v39
	s_mov_b32 s25, 0
	v_mov_b32_e32 v41, 0xf149f2ca
	v_mov_b32_e32 v13, 0
	s_cbranch_vccnz .LBB0_585
	s_mov_b32 s26, 1
	v_mov_b32_e32 v13, v38
	v_mov_b32_e32 v41, v39
